# P5 EpiUp + P6 EpiDown epilogues: loads batched/pipelined (5 rows of y in flight), counted vmcnt
# baseline (speedup 1.0000x reference)
; #define PG8_STAGE(bufoff, gbase, voff) do { _Pragma("unroll") for (int _i = 0; _i < 2; ++_i) \
;         __builtin_amdgcn_global_load_lds((const unsigned*)((const char*)(gbase) + (voff)[_i]), (PG8_LAS unsigned*)(lds + (bufoff) + ldsw + _i * 8192), 16, 0, 0); } while (0)
; #define PG8_LDA(dst, b, h) do { _Pragma("unroll") for (int m = 0; m < 4; ++m) _Pragma("unroll") for (int k = 0; k < 2; ++k) dst[m][k] = *(const PG8_LAS bf16x8*)(lds + PG8_SA(b, h) + aoff + m * 2048 + k * 1024); } while (0)
; #define PG8_LDB(dst, b, h) do { _Pragma("unroll") for (int n = 0; n < 2; ++n) _Pragma("unroll") for (int k = 0; k < 2; ++k) dst[n][k] = *(const PG8_LAS bf16x8*)(lds + PG8_SB(b, h) + boff + n * 2048 + k * 1024); } while (0)
; #define PG8_WAIT_V(n) asm volatile("s_waitcnt vmcnt(" #n ")" ::: "memory")
; #define PG8_WAIT_L(n) asm volatile("s_waitcnt lgkmcnt(" #n ")" ::: "memory")
; #define PG8_BAR __builtin_amdgcn_s_barrier()
; #define PG8_SCHED __builtin_amdgcn_sched_barrier(0)
; template <class Epi, class Sched, bool ALIGN_EPI = false, bool SP2 = false>
; __device__ __forceinline__ void gemm_phase(PG8_LAS unsigned char* lds, const Gemm g, const Sched& S, const Epi& E) {
;     ...
;         const bool has_next = S.next(ui + 1, nxt);
;         const char* nA = has_next ? (const char*)g.A + (size_t)nxt.pm * tstep : cA; const char* nB = has_next ? (const char*)g.Bt + (size_t)nxt.pn * tstep : cB;
;         for (int t = 0; t < nt; t += 2) {
;             const bool last = (t == nt - 2);
;             const char* a1 = cA + (size_t)(t + 1) * kstep;
;             const char* a2 = last ? nA : cA + (size_t)(t + 2) * kstep; const char* b2 = last ? nB : cB + (size_t)(t + 2) * kstep;
;             const char* a3 = a2 + kstep; const char* b3 = b2 + kstep;
;             if (last && has_next) S.a_ready(nxt);
;             if constexpr (SP2) {
;             PG8_LDB(B0, 0, 0); PG8_LDB(B1, 0, 1); PG8_SCHED; PG8_LDA(At, 0, 0); PG8_STAGE(PG8_SA(1, 1), a1 + hstep, voffA);
;             PG8_WAIT_V(8); PG8_WAIT_L(0); PG8_BAR; PG8_MMA(0, 0, At, B0); PG8_MMA(0, 1, At, B1); PG8_BAR; PG8_SCHED;
;             PG8_LDA(At, 0, 1); PG8_STAGE(PG8_SB(0, 0), b2, voffB); PG8_STAGE(PG8_SB(0, 1), b2 + hstep, voffB); PG8_STAGE(PG8_SA(0, 0), a2, voffA);
;             PG8_WAIT_V(8); PG8_WAIT_L(0); PG8_BAR; PG8_MMA(1, 0, At, B0); PG8_MMA(1, 1, At, B1); PG8_BAR; PG8_SCHED;
.LBB0_2136:
	ds_read_b128 v[152:155], v149
	ds_read_b128 v[156:159], v149 offset:1024
	ds_read_b128 v[160:163], v149 offset:2048
	ds_read_b128 v[164:167], v149 offset:3072
	ds_read_b128 v[168:171], v150
	ds_read_b128 v[172:175], v150 offset:1024
	ds_read_b128 v[176:179], v150 offset:2048
	ds_read_b128 v[180:183], v150 offset:3072
	s_add_u32 s30, s28, 0xfff00080
	s_addc_u32 s31, s29, -1
	s_cmp_eq_u32 s68, 60
	s_cselect_b32 s35, s21, s31
	s_cselect_b32 s34, s64, s30
	s_cselect_b32 s31, s19, s67
	s_cselect_b32 s30, s65, s66
	v_lshl_add_u64 v[144:145], s[28:29], 0, v[136:137]
	s_add_i32 m0, s27, 0xc000
	ds_read_b128 v[184:187], v151
	ds_read_b128 v[188:191], v151 offset:1024
	ds_read_b128 v[192:195], v151 offset:2048
	ds_read_b128 v[196:199], v151 offset:3072
	ds_read_b128 v[200:203], v151 offset:4096
	ds_read_b128 v[204:207], v151 offset:5120
	ds_read_b128 v[208:211], v151 offset:6144
	ds_read_b128 v[212:215], v151 offset:7168
	global_load_lds_dwordx4 v[144:145], off
	v_lshl_add_u64 v[144:145], s[28:29], 0, v[138:139]
	s_add_i32 m0, s27, 0xe000
	s_nop 0
	global_load_lds_dwordx4 v[144:145], off
	s_waitcnt vmcnt(8)
	s_waitcnt lgkmcnt(0)
	s_barrier
	s_setprio 1
	s_waitcnt lgkmcnt(0)
	v_mfma_f32_16x16x32_bf16 v[124:127], v[152:155], v[184:187], v[124:127]
	v_mfma_f32_16x16x32_bf16 v[120:123], v[160:163], v[184:187], v[120:123]
	v_mfma_f32_16x16x32_bf16 v[108:111], v[152:155], v[192:195], v[108:111]
	v_mfma_f32_16x16x32_bf16 v[104:107], v[160:163], v[192:195], v[104:107]
	v_mfma_f32_16x16x32_bf16 v[92:95], v[152:155], v[200:203], v[92:95]
	v_mfma_f32_16x16x32_bf16 v[88:91], v[160:163], v[200:203], v[88:91]
	v_mfma_f32_16x16x32_bf16 v[76:79], v[152:155], v[208:211], v[76:79]
	v_mfma_f32_16x16x32_bf16 v[72:75], v[160:163], v[208:211], v[72:75]
	v_mfma_f32_16x16x32_bf16 v[124:127], v[156:159], v[188:191], v[124:127]
	v_mfma_f32_16x16x32_bf16 v[120:123], v[164:167], v[188:191], v[120:123]
	v_mfma_f32_16x16x32_bf16 v[108:111], v[156:159], v[196:199], v[108:111]
	v_mfma_f32_16x16x32_bf16 v[104:107], v[164:167], v[196:199], v[104:107]
	v_mfma_f32_16x16x32_bf16 v[92:95], v[156:159], v[204:207], v[92:95]
	v_mfma_f32_16x16x32_bf16 v[88:91], v[164:167], v[204:207], v[88:91]
	v_mfma_f32_16x16x32_bf16 v[76:79], v[156:159], v[212:215], v[76:79]
	v_mfma_f32_16x16x32_bf16 v[72:75], v[164:167], v[212:215], v[72:75]
	s_setprio 0
	s_setprio 1
	v_mfma_f32_16x16x32_bf16 v[116:119], v[168:171], v[184:187], v[116:119]
	v_mfma_f32_16x16x32_bf16 v[112:115], v[176:179], v[184:187], v[112:115]
	v_mfma_f32_16x16x32_bf16 v[100:103], v[168:171], v[192:195], v[100:103]
	v_mfma_f32_16x16x32_bf16 v[96:99], v[176:179], v[192:195], v[96:99]
	v_mfma_f32_16x16x32_bf16 v[84:87], v[168:171], v[200:203], v[84:87]
	v_mfma_f32_16x16x32_bf16 v[80:83], v[176:179], v[200:203], v[80:83]
	v_mfma_f32_16x16x32_bf16 v[68:71], v[168:171], v[208:211], v[68:71]
	v_mfma_f32_16x16x32_bf16 v[64:67], v[176:179], v[208:211], v[64:67]
	v_mfma_f32_16x16x32_bf16 v[116:119], v[172:175], v[188:191], v[116:119]
	v_mfma_f32_16x16x32_bf16 v[112:115], v[180:183], v[188:191], v[112:115]
	v_mfma_f32_16x16x32_bf16 v[100:103], v[172:175], v[196:199], v[100:103]
	v_mfma_f32_16x16x32_bf16 v[96:99], v[180:183], v[196:199], v[96:99]
	v_mfma_f32_16x16x32_bf16 v[84:87], v[172:175], v[204:207], v[84:87]
	v_mfma_f32_16x16x32_bf16 v[80:83], v[180:183], v[204:207], v[80:83]
	v_mfma_f32_16x16x32_bf16 v[68:71], v[172:175], v[212:215], v[68:71]
	v_mfma_f32_16x16x32_bf16 v[64:67], v[180:183], v[212:215], v[64:67]
	s_setprio 0
	s_barrier
	s_add_i32 s69, s51, s39
	v_lshl_add_u64 v[144:145], s[30:31], 0, v[132:133]
	s_mov_b32 m0, s69
	ds_read_b128 v[184:187], v151 offset:16384
	ds_read_b128 v[188:191], v151 offset:17408
	ds_read_b128 v[192:195], v151 offset:18432
	ds_read_b128 v[196:199], v151 offset:19456
	ds_read_b128 v[200:203], v151 offset:20480
	ds_read_b128 v[204:207], v151 offset:21504
	ds_read_b128 v[208:211], v151 offset:22528
	ds_read_b128 v[212:215], v151 offset:23552
	global_load_lds_dwordx4 v[144:145], off
	s_add_i32 m0, s69, 0x2000
	s_add_u32 s70, s30, 0x100000
	v_lshl_add_u64 v[216:217], s[30:31], 0, v[128:129]
	s_addc_u32 s71, s31, 0
	s_add_i32 s69, s52, s39
	global_load_lds_dwordx4 v[216:217], off
	v_lshl_add_u64 v[218:219], s[70:71], 0, v[132:133]
	s_mov_b32 m0, s69
	v_lshl_add_u64 v[220:221], s[34:35], 0, v[130:131]
	global_load_lds_dwordx4 v[218:219], off
	v_lshl_add_u64 v[218:219], s[70:71], 0, v[128:129]
	s_add_i32 m0, s69, 0x2000
	s_nop 0
	global_load_lds_dwordx4 v[218:219], off
	v_lshl_add_u64 v[218:219], s[34:35], 0, v[134:135]
	s_mov_b32 m0, s27
	s_nop 0
	global_load_lds_dwordx4 v[218:219], off
	s_mov_b32 m0, s42
	s_nop 0
	global_load_lds_dwordx4 v[220:221], off
	s_waitcnt vmcnt(8)
	s_waitcnt lgkmcnt(0)
	s_barrier
; #define PG8_STAGE(bufoff, gbase, voff) do { _Pragma("unroll") for (int _i = 0; _i < 2; ++_i) \
;         __builtin_amdgcn_global_load_lds((const unsigned*)((const char*)(gbase) + (voff)[_i]), (PG8_LAS unsigned*)(lds + (bufoff) + ldsw + _i * 8192), 16, 0, 0); } while (0)
; #define PG8_LDA(dst, b, h) do { _Pragma("unroll") for (int m = 0; m < 4; ++m) _Pragma("unroll") for (int k = 0; k < 2; ++k) dst[m][k] = *(const PG8_LAS bf16x8*)(lds + PG8_SA(b, h) + aoff + m * 2048 + k * 1024); } while (0)
; #define PG8_LDB(dst, b, h) do { _Pragma("unroll") for (int n = 0; n < 2; ++n) _Pragma("unroll") for (int k = 0; k < 2; ++k) dst[n][k] = *(const PG8_LAS bf16x8*)(lds + PG8_SB(b, h) + boff + n * 2048 + k * 1024); } while (0)
; #define PG8_MMA(ai, bj, At, Bt) do { __builtin_amdgcn_s_setprio(1); _Pragma("unroll") for (int m = 0; m < 4; ++m) _Pragma("unroll") for (int n = 0; n < 2; ++n) _Pragma("unroll") for (int k = 0; k < 2; ++k) \
;         acc[ai][bj][m][n] = __builtin_amdgcn_mfma_f32_16x16x32_bf16(Bt[n][k], At[m][k], acc[ai][bj][m][n], 0, 0, 0); __builtin_amdgcn_s_setprio(0); } while (0)
; #define PG8_WAIT_V(n) asm volatile("s_waitcnt vmcnt(" #n ")" ::: "memory")
; #define PG8_WAIT_L(n) asm volatile("s_waitcnt lgkmcnt(" #n ")" ::: "memory")
; #define PG8_BAR __builtin_amdgcn_s_barrier()
; #define PG8_SCHED __builtin_amdgcn_sched_barrier(0)
; template <class Epi, class Sched, bool ALIGN_EPI = false, bool SP2 = false>
; __device__ __forceinline__ void gemm_phase(PG8_LAS unsigned char* lds, const Gemm g, const Sched& S, const Epi& E) {
;     ...
;             PG8_WAIT_V(8); PG8_WAIT_L(0); PG8_BAR; PG8_MMA(1, 0, At, B0); PG8_MMA(1, 1, At, B1); PG8_BAR; PG8_SCHED;
;             PG8_LDB(B0, 1, 0); PG8_LDB(B1, 1, 1); PG8_SCHED; PG8_LDA(At, 1, 0); PG8_STAGE(PG8_SA(0, 1), a2 + hstep, voffA);
;             PG8_WAIT_V(8); PG8_WAIT_L(0); PG8_BAR; PG8_MMA(0, 0, At, B0); PG8_MMA(0, 1, At, B1); PG8_BAR; PG8_SCHED;
	s_setprio 1
	s_waitcnt lgkmcnt(0)
	v_mfma_f32_16x16x32_bf16 v[60:63], v[152:155], v[184:187], v[60:63]
	v_mfma_f32_16x16x32_bf16 v[56:59], v[160:163], v[184:187], v[56:59]
	v_mfma_f32_16x16x32_bf16 v[44:47], v[152:155], v[192:195], v[44:47]
	v_mfma_f32_16x16x32_bf16 v[40:43], v[160:163], v[192:195], v[40:43]
	v_mfma_f32_16x16x32_bf16 v[28:31], v[152:155], v[200:203], v[28:31]
	v_mfma_f32_16x16x32_bf16 v[24:27], v[160:163], v[200:203], v[24:27]
	v_mfma_f32_16x16x32_bf16 v[12:15], v[152:155], v[208:211], v[12:15]
	v_mfma_f32_16x16x32_bf16 v[8:11], v[160:163], v[208:211], v[8:11]
	v_mfma_f32_16x16x32_bf16 v[60:63], v[156:159], v[188:191], v[60:63]
	v_mfma_f32_16x16x32_bf16 v[56:59], v[164:167], v[188:191], v[56:59]
	v_mfma_f32_16x16x32_bf16 v[44:47], v[156:159], v[196:199], v[44:47]
	v_mfma_f32_16x16x32_bf16 v[40:43], v[164:167], v[196:199], v[40:43]
	v_mfma_f32_16x16x32_bf16 v[28:31], v[156:159], v[204:207], v[28:31]
	v_mfma_f32_16x16x32_bf16 v[24:27], v[164:167], v[204:207], v[24:27]
	v_mfma_f32_16x16x32_bf16 v[12:15], v[156:159], v[212:215], v[12:15]
	v_mfma_f32_16x16x32_bf16 v[8:11], v[164:167], v[212:215], v[8:11]
	s_setprio 0
	s_setprio 1
	v_mfma_f32_16x16x32_bf16 v[52:55], v[168:171], v[184:187], v[52:55]
	v_mfma_f32_16x16x32_bf16 v[48:51], v[176:179], v[184:187], v[48:51]
	v_mfma_f32_16x16x32_bf16 v[36:39], v[168:171], v[192:195], v[36:39]
	v_mfma_f32_16x16x32_bf16 v[32:35], v[176:179], v[192:195], v[32:35]
	v_mfma_f32_16x16x32_bf16 v[20:23], v[168:171], v[200:203], v[20:23]
	v_mfma_f32_16x16x32_bf16 v[16:19], v[176:179], v[200:203], v[16:19]
	v_mfma_f32_16x16x32_bf16 v[4:7], v[168:171], v[208:211], v[4:7]
	v_mfma_f32_16x16x32_bf16 v[0:3], v[176:179], v[208:211], v[0:3]
	v_mfma_f32_16x16x32_bf16 v[52:55], v[172:175], v[188:191], v[52:55]
	v_mfma_f32_16x16x32_bf16 v[48:51], v[180:183], v[188:191], v[48:51]
	v_mfma_f32_16x16x32_bf16 v[36:39], v[172:175], v[196:199], v[36:39]
	v_mfma_f32_16x16x32_bf16 v[32:35], v[180:183], v[196:199], v[32:35]
	v_mfma_f32_16x16x32_bf16 v[20:23], v[172:175], v[204:207], v[20:23]
	v_mfma_f32_16x16x32_bf16 v[16:19], v[180:183], v[204:207], v[16:19]
	v_mfma_f32_16x16x32_bf16 v[4:7], v[172:175], v[212:215], v[4:7]
	v_mfma_f32_16x16x32_bf16 v[0:3], v[180:183], v[212:215], v[0:3]
	s_setprio 0
	s_barrier
	s_add_i32 s69, 0, 0x18000
	s_add_i32 s70, 0, 0x1c000
	v_add_u32_e32 v164, s69, v147
	v_add_u32_e32 v180, s70, v147
	ds_read_b128 v[152:155], v164
	ds_read_b128 v[156:159], v164 offset:1024
	ds_read_b128 v[160:163], v164 offset:2048
	ds_read_b128 v[164:167], v164 offset:3072
	ds_read_b128 v[168:171], v180
	ds_read_b128 v[172:175], v180 offset:1024
	ds_read_b128 v[176:179], v180 offset:2048
	ds_read_b128 v[180:183], v180 offset:3072
	s_add_u32 s34, s34, 0x100000
	s_addc_u32 s35, s35, 0
	s_mov_b32 m0, s43
	v_lshl_add_u64 v[222:223], s[34:35], 0, v[134:135]
	ds_read_b128 v[184:187], v151 offset:32768
	ds_read_b128 v[188:191], v151 offset:33792
	ds_read_b128 v[192:195], v151 offset:34816
	ds_read_b128 v[196:199], v151 offset:35840
	ds_read_b128 v[200:203], v151 offset:36864
	ds_read_b128 v[204:207], v151 offset:37888
	ds_read_b128 v[208:211], v151 offset:38912
	ds_read_b128 v[212:215], v151 offset:39936
	global_load_lds_dwordx4 v[222:223], off
	v_lshl_add_u64 v[222:223], s[34:35], 0, v[130:131]
	s_mov_b32 m0, s46
	s_nop 0
	global_load_lds_dwordx4 v[222:223], off
	s_waitcnt vmcnt(8)
	s_waitcnt lgkmcnt(0)
	s_barrier
	s_setprio 1
	s_waitcnt lgkmcnt(0)
	v_mfma_f32_16x16x32_bf16 v[124:127], v[152:155], v[184:187], v[124:127]
	v_mfma_f32_16x16x32_bf16 v[120:123], v[160:163], v[184:187], v[120:123]
	v_mfma_f32_16x16x32_bf16 v[108:111], v[152:155], v[192:195], v[108:111]
	v_mfma_f32_16x16x32_bf16 v[104:107], v[160:163], v[192:195], v[104:107]
	v_mfma_f32_16x16x32_bf16 v[92:95], v[152:155], v[200:203], v[92:95]
	v_mfma_f32_16x16x32_bf16 v[88:91], v[160:163], v[200:203], v[88:91]
	v_mfma_f32_16x16x32_bf16 v[76:79], v[152:155], v[208:211], v[76:79]
	v_mfma_f32_16x16x32_bf16 v[72:75], v[160:163], v[208:211], v[72:75]
	v_mfma_f32_16x16x32_bf16 v[124:127], v[156:159], v[188:191], v[124:127]
	v_mfma_f32_16x16x32_bf16 v[120:123], v[164:167], v[188:191], v[120:123]
	v_mfma_f32_16x16x32_bf16 v[108:111], v[156:159], v[196:199], v[108:111]
	v_mfma_f32_16x16x32_bf16 v[104:107], v[164:167], v[196:199], v[104:107]
	v_mfma_f32_16x16x32_bf16 v[92:95], v[156:159], v[204:207], v[92:95]
	v_mfma_f32_16x16x32_bf16 v[88:91], v[164:167], v[204:207], v[88:91]
	v_mfma_f32_16x16x32_bf16 v[76:79], v[156:159], v[212:215], v[76:79]
	v_mfma_f32_16x16x32_bf16 v[72:75], v[164:167], v[212:215], v[72:75]
	s_setprio 0
	s_setprio 1
	v_mfma_f32_16x16x32_bf16 v[116:119], v[168:171], v[184:187], v[116:119]
	v_mfma_f32_16x16x32_bf16 v[112:115], v[176:179], v[184:187], v[112:115]
	v_mfma_f32_16x16x32_bf16 v[100:103], v[168:171], v[192:195], v[100:103]
	v_mfma_f32_16x16x32_bf16 v[96:99], v[176:179], v[192:195], v[96:99]
	v_mfma_f32_16x16x32_bf16 v[84:87], v[168:171], v[200:203], v[84:87]
	v_mfma_f32_16x16x32_bf16 v[80:83], v[176:179], v[200:203], v[80:83]
	v_mfma_f32_16x16x32_bf16 v[68:71], v[168:171], v[208:211], v[68:71]
	v_mfma_f32_16x16x32_bf16 v[64:67], v[176:179], v[208:211], v[64:67]
	v_mfma_f32_16x16x32_bf16 v[116:119], v[172:175], v[188:191], v[116:119]
	v_mfma_f32_16x16x32_bf16 v[112:115], v[180:183], v[188:191], v[112:115]
	v_mfma_f32_16x16x32_bf16 v[100:103], v[172:175], v[196:199], v[100:103]
	v_mfma_f32_16x16x32_bf16 v[96:99], v[180:183], v[196:199], v[96:99]
	v_mfma_f32_16x16x32_bf16 v[84:87], v[172:175], v[204:207], v[84:87]
	v_mfma_f32_16x16x32_bf16 v[80:83], v[180:183], v[204:207], v[80:83]
	v_mfma_f32_16x16x32_bf16 v[68:71], v[172:175], v[212:215], v[68:71]
	v_mfma_f32_16x16x32_bf16 v[64:67], v[180:183], v[212:215], v[64:67]
	s_setprio 0
	s_barrier
; #define PG8_STAGE(bufoff, gbase, voff) do { _Pragma("unroll") for (int _i = 0; _i < 2; ++_i) \
;         __builtin_amdgcn_global_load_lds((const unsigned*)((const char*)(gbase) + (voff)[_i]), (PG8_LAS unsigned*)(lds + (bufoff) + ldsw + _i * 8192), 16, 0, 0); } while (0)
; #define PG8_LDA(dst, b, h) do { _Pragma("unroll") for (int m = 0; m < 4; ++m) _Pragma("unroll") for (int k = 0; k < 2; ++k) dst[m][k] = *(const PG8_LAS bf16x8*)(lds + PG8_SA(b, h) + aoff + m * 2048 + k * 1024); } while (0)
; #define PG8_MMA(ai, bj, At, Bt) do { __builtin_amdgcn_s_setprio(1); _Pragma("unroll") for (int m = 0; m < 4; ++m) _Pragma("unroll") for (int n = 0; n < 2; ++n) _Pragma("unroll") for (int k = 0; k < 2; ++k) \
;         acc[ai][bj][m][n] = __builtin_amdgcn_mfma_f32_16x16x32_bf16(Bt[n][k], At[m][k], acc[ai][bj][m][n], 0, 0, 0); __builtin_amdgcn_s_setprio(0); } while (0)
; #define PG8_WAIT_V(n) asm volatile("s_waitcnt vmcnt(" #n ")" ::: "memory")
; #define PG8_WAIT_L(n) asm volatile("s_waitcnt lgkmcnt(" #n ")" ::: "memory")
; #define PG8_BAR __builtin_amdgcn_s_barrier()
; #define PG8_SCHED __builtin_amdgcn_sched_barrier(0)
; template <class Epi, class Sched, bool ALIGN_EPI = false, bool SP2 = false>
; __device__ __forceinline__ void gemm_phase(PG8_LAS unsigned char* lds, const Gemm g, const Sched& S, const Epi& E) {
;     ...
;             PG8_LDA(At, 1, 1); PG8_STAGE(PG8_SB(1, 0), b3, voffB); PG8_STAGE(PG8_SB(1, 1), b3 + hstep, voffB); PG8_STAGE(PG8_SA(1, 0), a3, voffA);
;             PG8_WAIT_V(8); PG8_WAIT_L(0); PG8_BAR; PG8_MMA(1, 0, At, B0); PG8_MMA(1, 1, At, B1); PG8_BAR; PG8_SCHED;
;     __device__ __forceinline__ void operator()(const f32x4 (&acc)[2][2][4][2], const Unit& u, int wr, int wc, int fr, int fq) const {
;         const int rbase = u.pm * 256 + wr * 64 + fr, cb = u.pn * 256 + wc * 32 + fq * 8;
; #pragma unroll
;         for (int ai = 0; ai < 2; ++ai)
; #pragma unroll
;             for (int m = 0; m < 4; ++m) { float* yr = y + (size_t)(rbase + ai * 128 + m * 16) * 1024 + cb;
; #pragma unroll
;                 for (int bj = 0; bj < 2; ++bj) { float* yp = yr + bj * 128; const f32x4 a = *(const f32x4*)yp + acc[ai][bj][m][0], b = *(const f32x4*)(yp + 4) + acc[ai][bj][m][1]; *(f32x4*)yp = a; *(f32x4*)(yp + 4) = b; }
	s_add_i32 s34, s69, s39
	v_lshl_add_u64 v[144:145], v[144:145], 0, s[6:7]
	s_mov_b32 m0, s34
	ds_read_b128 v[184:187], v151 offset:49152
	ds_read_b128 v[188:191], v151 offset:50176
	ds_read_b128 v[192:195], v151 offset:51200
	ds_read_b128 v[196:199], v151 offset:52224
	ds_read_b128 v[200:203], v151 offset:53248
	ds_read_b128 v[204:207], v151 offset:54272
	ds_read_b128 v[208:211], v151 offset:55296
	ds_read_b128 v[212:215], v151 offset:56320
	global_load_lds_dwordx4 v[144:145], off
	s_add_i32 m0, s34, 0x2000
	s_add_u32 s30, s30, 0x100080
	v_lshl_add_u64 v[144:145], v[216:217], 0, s[6:7]
	s_addc_u32 s31, s31, 0
	s_add_i32 s34, s70, s39
	global_load_lds_dwordx4 v[144:145], off
	v_lshl_add_u64 v[144:145], s[30:31], 0, v[132:133]
	s_mov_b32 m0, s34
	s_nop 0
	global_load_lds_dwordx4 v[144:145], off
	v_lshl_add_u64 v[144:145], s[30:31], 0, v[128:129]
	s_add_i32 m0, s34, 0x2000
	s_nop 0
	global_load_lds_dwordx4 v[144:145], off
	v_lshl_add_u64 v[144:145], v[218:219], 0, s[6:7]
	s_mov_b32 m0, s48
	s_nop 0
	global_load_lds_dwordx4 v[144:145], off
	v_lshl_add_u64 v[144:145], v[220:221], 0, s[6:7]
	s_mov_b32 m0, s49
	s_nop 0
	global_load_lds_dwordx4 v[144:145], off
	s_waitcnt vmcnt(8)
	s_waitcnt lgkmcnt(0)
	s_barrier
	s_setprio 1
	s_waitcnt lgkmcnt(0)
	v_mfma_f32_16x16x32_bf16 v[60:63], v[152:155], v[184:187], v[60:63]
	v_mfma_f32_16x16x32_bf16 v[56:59], v[160:163], v[184:187], v[56:59]
	v_mfma_f32_16x16x32_bf16 v[44:47], v[152:155], v[192:195], v[44:47]
	v_mfma_f32_16x16x32_bf16 v[40:43], v[160:163], v[192:195], v[40:43]
	v_mfma_f32_16x16x32_bf16 v[28:31], v[152:155], v[200:203], v[28:31]
	v_mfma_f32_16x16x32_bf16 v[24:27], v[160:163], v[200:203], v[24:27]
	v_mfma_f32_16x16x32_bf16 v[12:15], v[152:155], v[208:211], v[12:15]
	v_mfma_f32_16x16x32_bf16 v[8:11], v[160:163], v[208:211], v[8:11]
	v_mfma_f32_16x16x32_bf16 v[60:63], v[156:159], v[188:191], v[60:63]
	v_mfma_f32_16x16x32_bf16 v[56:59], v[164:167], v[188:191], v[56:59]
	v_mfma_f32_16x16x32_bf16 v[44:47], v[156:159], v[196:199], v[44:47]
	v_mfma_f32_16x16x32_bf16 v[40:43], v[164:167], v[196:199], v[40:43]
	v_mfma_f32_16x16x32_bf16 v[28:31], v[156:159], v[204:207], v[28:31]
	v_mfma_f32_16x16x32_bf16 v[24:27], v[164:167], v[204:207], v[24:27]
	v_mfma_f32_16x16x32_bf16 v[12:15], v[156:159], v[212:215], v[12:15]
	v_mfma_f32_16x16x32_bf16 v[8:11], v[164:167], v[212:215], v[8:11]
	s_setprio 0
	s_setprio 1
	v_mfma_f32_16x16x32_bf16 v[52:55], v[168:171], v[184:187], v[52:55]
	v_mfma_f32_16x16x32_bf16 v[48:51], v[176:179], v[184:187], v[48:51]
	v_mfma_f32_16x16x32_bf16 v[36:39], v[168:171], v[192:195], v[36:39]
	v_mfma_f32_16x16x32_bf16 v[32:35], v[176:179], v[192:195], v[32:35]
	v_mfma_f32_16x16x32_bf16 v[20:23], v[168:171], v[200:203], v[20:23]
	v_mfma_f32_16x16x32_bf16 v[16:19], v[176:179], v[200:203], v[16:19]
	v_mfma_f32_16x16x32_bf16 v[4:7], v[168:171], v[208:211], v[4:7]
	v_mfma_f32_16x16x32_bf16 v[0:3], v[176:179], v[208:211], v[0:3]
	v_mfma_f32_16x16x32_bf16 v[52:55], v[172:175], v[188:191], v[52:55]
	v_mfma_f32_16x16x32_bf16 v[48:51], v[180:183], v[188:191], v[48:51]
	v_mfma_f32_16x16x32_bf16 v[36:39], v[172:175], v[196:199], v[36:39]
	v_mfma_f32_16x16x32_bf16 v[32:35], v[180:183], v[196:199], v[32:35]
	v_mfma_f32_16x16x32_bf16 v[20:23], v[172:175], v[204:207], v[20:23]
	v_mfma_f32_16x16x32_bf16 v[16:19], v[180:183], v[204:207], v[16:19]
	v_mfma_f32_16x16x32_bf16 v[4:7], v[172:175], v[212:215], v[4:7]
	v_mfma_f32_16x16x32_bf16 v[0:3], v[180:183], v[212:215], v[0:3]
	s_setprio 0
	s_barrier
	s_add_i32 s68, s68, 2
	s_add_u32 s28, s28, 0x100
	s_addc_u32 s29, s29, 0
	s_add_u32 s66, s66, 0x100
	s_addc_u32 s67, s67, 0
	s_cmp_gt_u32 s68, 61
	s_cbranch_scc0 .LBB0_2136
	v_lshl_add_u32 v216, s26, 8, v146
	v_lshl_or_b32 v218, s63, 8, v148
	v_ashrrev_i32_e32 v217, 31, v216
	v_ashrrev_i32_e32 v219, 31, v218
	v_lshlrev_b64 v[216:217], 12, v[216:217]
	v_lshlrev_b64 v[218:219], 2, v[218:219]
	v_lshl_add_u64 v[216:217], s[84:85], 0, v[216:217]
	v_lshl_add_u64 v[216:217], v[216:217], 0, v[218:219]
	v_mov_b64_e32 v[218:219], v[216:217]
	s_mov_b64 s[98:99], 0x10000
	s_mov_b64 s[100:101], 0x50000
	global_load_dwordx4 v[152:155], v[216:217], off
	global_load_dwordx4 v[156:159], v[216:217], off offset:16
	global_load_dwordx4 v[160:163], v[216:217], off offset:512
	global_load_dwordx4 v[164:167], v[216:217], off offset:528
	v_lshl_add_u64 v[216:217], v[216:217], 0, s[98:99]
	global_load_dwordx4 v[168:171], v[216:217], off
	global_load_dwordx4 v[172:175], v[216:217], off offset:16
	global_load_dwordx4 v[176:179], v[216:217], off offset:512
	global_load_dwordx4 v[180:183], v[216:217], off offset:528
	v_lshl_add_u64 v[216:217], v[216:217], 0, s[98:99]
	global_load_dwordx4 v[184:187], v[216:217], off
	global_load_dwordx4 v[188:191], v[216:217], off offset:16
	global_load_dwordx4 v[192:195], v[216:217], off offset:512
	global_load_dwordx4 v[196:199], v[216:217], off offset:528
	v_lshl_add_u64 v[216:217], v[216:217], 0, s[98:99]
	global_load_dwordx4 v[200:203], v[216:217], off
	global_load_dwordx4 v[204:207], v[216:217], off offset:16
	global_load_dwordx4 v[208:211], v[216:217], off offset:512
	global_load_dwordx4 v[212:215], v[216:217], off offset:528
	v_lshl_add_u64 v[216:217], v[216:217], 0, s[100:101]
	global_load_dwordx4 v[228:231], v[216:217], off
	global_load_dwordx4 v[232:235], v[216:217], off offset:16
	global_load_dwordx4 v[236:239], v[216:217], off offset:512
	global_load_dwordx4 v[240:243], v[216:217], off offset:528
	v_lshl_add_u64 v[216:217], v[216:217], 0, s[98:99]
	s_and_b64 vcc, exec, s[8:9]
	s_cbranch_vccz .LBB0_2139
	s_barrier
;     __device__ __forceinline__ void operator()(const f32x4 (&acc)[2][2][4][2], const Unit& u, int wr, int wc, int fr, int fq) const {
;         const int rbase = u.pm * 256 + wr * 64 + fr, cb = u.pn * 256 + wc * 32 + fq * 8;
; #pragma unroll
;         for (int ai = 0; ai < 2; ++ai)
; #pragma unroll
;             for (int m = 0; m < 4; ++m) { float* yr = y + (size_t)(rbase + ai * 128 + m * 16) * 1024 + cb;
; #pragma unroll
;                 for (int bj = 0; bj < 2; ++bj) { float* yp = yr + bj * 128; const f32x4 a = *(const f32x4*)yp + acc[ai][bj][m][0], b = *(const f32x4*)(yp + 4) + acc[ai][bj][m][1]; *(f32x4*)yp = a; *(f32x4*)(yp + 4) = b; }
;                 asm volatile("" ::: "memory"); }
.LBB0_2139:
	s_waitcnt vmcnt(16)
	v_pk_add_f32 v[124:125], v[124:125], v[152:153]
	v_pk_add_f32 v[126:127], v[126:127], v[154:155]
	v_pk_add_f32 v[120:121], v[120:121], v[156:157]
	v_pk_add_f32 v[122:123], v[122:123], v[158:159]
	v_pk_add_f32 v[116:117], v[116:117], v[160:161]
	v_pk_add_f32 v[118:119], v[118:119], v[162:163]
	v_pk_add_f32 v[112:113], v[112:113], v[164:165]
	v_pk_add_f32 v[114:115], v[114:115], v[166:167]
	global_store_dwordx4 v[218:219], v[124:127], off
	global_store_dwordx4 v[218:219], v[120:123], off offset:16
	global_store_dwordx4 v[218:219], v[116:119], off offset:512
	global_store_dwordx4 v[218:219], v[112:115], off offset:528
	v_lshl_add_u64 v[218:219], v[218:219], 0, s[98:99]
	global_load_dwordx4 v[152:155], v[216:217], off
	global_load_dwordx4 v[156:159], v[216:217], off offset:16
	global_load_dwordx4 v[160:163], v[216:217], off offset:512
	global_load_dwordx4 v[164:167], v[216:217], off offset:528
	v_lshl_add_u64 v[216:217], v[216:217], 0, s[98:99]
	s_waitcnt vmcnt(20)
	v_pk_add_f32 v[108:109], v[108:109], v[168:169]
	v_pk_add_f32 v[110:111], v[110:111], v[170:171]
	v_pk_add_f32 v[104:105], v[104:105], v[172:173]
	v_pk_add_f32 v[106:107], v[106:107], v[174:175]
	v_pk_add_f32 v[100:101], v[100:101], v[176:177]
	v_pk_add_f32 v[102:103], v[102:103], v[178:179]
	v_pk_add_f32 v[96:97], v[96:97], v[180:181]
	v_pk_add_f32 v[98:99], v[98:99], v[182:183]
	global_store_dwordx4 v[218:219], v[108:111], off
	global_store_dwordx4 v[218:219], v[104:107], off offset:16
	global_store_dwordx4 v[218:219], v[100:103], off offset:512
	global_store_dwordx4 v[218:219], v[96:99], off offset:528
	v_lshl_add_u64 v[218:219], v[218:219], 0, s[98:99]
	global_load_dwordx4 v[168:171], v[216:217], off
	global_load_dwordx4 v[172:175], v[216:217], off offset:16
	global_load_dwordx4 v[176:179], v[216:217], off offset:512
	global_load_dwordx4 v[180:183], v[216:217], off offset:528
	v_lshl_add_u64 v[216:217], v[216:217], 0, s[98:99]
	s_waitcnt vmcnt(24)
	v_pk_add_f32 v[92:93], v[92:93], v[184:185]
	v_pk_add_f32 v[94:95], v[94:95], v[186:187]
	v_pk_add_f32 v[88:89], v[88:89], v[188:189]
	v_pk_add_f32 v[90:91], v[90:91], v[190:191]
	v_pk_add_f32 v[84:85], v[84:85], v[192:193]
	v_pk_add_f32 v[86:87], v[86:87], v[194:195]
	v_pk_add_f32 v[80:81], v[80:81], v[196:197]
	v_pk_add_f32 v[82:83], v[82:83], v[198:199]
	global_store_dwordx4 v[218:219], v[92:95], off
	global_store_dwordx4 v[218:219], v[88:91], off offset:16
	global_store_dwordx4 v[218:219], v[84:87], off offset:512
	global_store_dwordx4 v[218:219], v[80:83], off offset:528
	v_lshl_add_u64 v[218:219], v[218:219], 0, s[98:99]
	global_load_dwordx4 v[184:187], v[216:217], off
	global_load_dwordx4 v[188:191], v[216:217], off offset:16
	global_load_dwordx4 v[192:195], v[216:217], off offset:512
	global_load_dwordx4 v[196:199], v[216:217], off offset:528
	s_waitcnt vmcnt(28)
	v_pk_add_f32 v[76:77], v[76:77], v[200:201]
	v_pk_add_f32 v[78:79], v[78:79], v[202:203]
	v_pk_add_f32 v[72:73], v[72:73], v[204:205]
	v_pk_add_f32 v[74:75], v[74:75], v[206:207]
	v_pk_add_f32 v[68:69], v[68:69], v[208:209]
	v_pk_add_f32 v[70:71], v[70:71], v[210:211]
	v_pk_add_f32 v[64:65], v[64:65], v[212:213]
	v_pk_add_f32 v[66:67], v[66:67], v[214:215]
	global_store_dwordx4 v[218:219], v[76:79], off
	global_store_dwordx4 v[218:219], v[72:75], off offset:16
	global_store_dwordx4 v[218:219], v[68:71], off offset:512
	global_store_dwordx4 v[218:219], v[64:67], off offset:528
	v_lshl_add_u64 v[218:219], v[218:219], 0, s[100:101]
	s_waitcnt vmcnt(28)
	v_pk_add_f32 v[60:61], v[60:61], v[228:229]
	v_pk_add_f32 v[62:63], v[62:63], v[230:231]
	v_pk_add_f32 v[56:57], v[56:57], v[232:233]
	v_pk_add_f32 v[58:59], v[58:59], v[234:235]
	v_pk_add_f32 v[52:53], v[52:53], v[236:237]
	v_pk_add_f32 v[54:55], v[54:55], v[238:239]
	v_pk_add_f32 v[48:49], v[48:49], v[240:241]
	v_pk_add_f32 v[50:51], v[50:51], v[242:243]
	global_store_dwordx4 v[218:219], v[60:63], off
	global_store_dwordx4 v[218:219], v[56:59], off offset:16
	global_store_dwordx4 v[218:219], v[52:55], off offset:512
	global_store_dwordx4 v[218:219], v[48:51], off offset:528
	v_lshl_add_u64 v[218:219], v[218:219], 0, s[98:99]
	s_waitcnt vmcnt(24)
	v_pk_add_f32 v[44:45], v[44:45], v[152:153]
	v_pk_add_f32 v[46:47], v[46:47], v[154:155]
	v_pk_add_f32 v[40:41], v[40:41], v[156:157]
	v_pk_add_f32 v[42:43], v[42:43], v[158:159]
	v_pk_add_f32 v[36:37], v[36:37], v[160:161]
	v_pk_add_f32 v[38:39], v[38:39], v[162:163]
	v_pk_add_f32 v[32:33], v[32:33], v[164:165]
	v_pk_add_f32 v[34:35], v[34:35], v[166:167]
	global_store_dwordx4 v[218:219], v[44:47], off
	global_store_dwordx4 v[218:219], v[40:43], off offset:16
	global_store_dwordx4 v[218:219], v[36:39], off offset:512
	global_store_dwordx4 v[218:219], v[32:35], off offset:528
	v_lshl_add_u64 v[218:219], v[218:219], 0, s[98:99]
	s_waitcnt vmcnt(20)
	v_pk_add_f32 v[28:29], v[28:29], v[168:169]
	v_pk_add_f32 v[30:31], v[30:31], v[170:171]
	v_pk_add_f32 v[24:25], v[24:25], v[172:173]
	v_pk_add_f32 v[26:27], v[26:27], v[174:175]
	v_pk_add_f32 v[20:21], v[20:21], v[176:177]
	v_pk_add_f32 v[22:23], v[22:23], v[178:179]
	v_pk_add_f32 v[16:17], v[16:17], v[180:181]
	v_pk_add_f32 v[18:19], v[18:19], v[182:183]
	global_store_dwordx4 v[218:219], v[28:31], off
	global_store_dwordx4 v[218:219], v[24:27], off offset:16
	global_store_dwordx4 v[218:219], v[20:23], off offset:512
	global_store_dwordx4 v[218:219], v[16:19], off offset:528
	v_lshl_add_u64 v[218:219], v[218:219], 0, s[98:99]
	s_waitcnt vmcnt(16)
	v_pk_add_f32 v[12:13], v[12:13], v[184:185]
	v_pk_add_f32 v[14:15], v[14:15], v[186:187]
	v_pk_add_f32 v[8:9], v[8:9], v[188:189]
	v_pk_add_f32 v[10:11], v[10:11], v[190:191]
	v_pk_add_f32 v[4:5], v[4:5], v[192:193]
	v_pk_add_f32 v[6:7], v[6:7], v[194:195]
	v_pk_add_f32 v[0:1], v[0:1], v[196:197]
	v_pk_add_f32 v[2:3], v[2:3], v[198:199]
	global_store_dwordx4 v[218:219], v[12:15], off
	global_store_dwordx4 v[218:219], v[8:11], off offset:16
	global_store_dwordx4 v[218:219], v[4:7], off offset:512
	global_store_dwordx4 v[218:219], v[0:3], off offset:528
	s_andn2_b64 vcc, exec, s[0:1]
	s_mov_b64 s[0:1], -1
	s_cbranch_vccnz .LBB0_2132
	s_andn2_b64 vcc, exec, s[4:5]
	s_cbranch_vccnz .LBB0_2131
	s_barrier
	s_branch .LBB0_2131
